# v31 plus priority 2 for the waves whose static first unit is among the 64 heaviest
# baseline (speedup 1.0000x reference)
.LBB0_350:
	s_cmp_lt_i32 s99, 0
	s_cbranch_scc1 .Lq_pop
	v_mov_b32_e32 v0, s99
	s_cmpk_lt_u32 s99, 0x40
	s_cbranch_scc0 .Lq_noprio
	s_setprio 2
.Lq_noprio:
	s_mov_b32 s99, -1
	s_branch .Lq_have
.Lq_pop:
	s_setprio 0
	v_mov_b32_e32 v0, 0
	s_and_saveexec_b64 s[4:5], s[18:19]
	s_cbranch_execz .LBB0_354
	s_mov_b64 s[8:9], exec
	v_mbcnt_lo_u32_b32 v0, s8, 0
	v_mbcnt_hi_u32_b32 v0, s9, v0
	v_cmp_eq_u32_e32 vcc, 0, v0
	s_and_saveexec_b64 s[6:7], vcc
	s_cbranch_execz .LBB0_353
	s_bcnt1_i32_b64 s3, s[8:9]
	v_mov_b32_e32 v2, s3
	global_atomic_add v2, v1, v2, s[40:41] offset:256 sc0
